# tail-first for workgroups with bit 3 of the id set (alternating inside each XCD) in P8/P9/P10/P11
# baseline (speedup 1.0000x reference)
.Ltf_P8_redo:
	s_add_u32 s20, s28, 0x7e80000
	s_addc_u32 s21, s29, 0
	s_add_u32 s4, s28, 0x2300000
	s_addc_u32 s5, s29, 0
	v_and_b32_e32 v168, 0x3ff, v0
	s_cmpk_lt_i32 s2, 0x100
	s_cselect_b64 s[6:7], -1, 0
	s_cmpk_gt_i32 s2, 0xff
	v_readfirstlane_b32 s12, v168
	s_cmp_lg_u32 s100, 0
	s_cbranch_scc1 .Ltf_P8_go
	s_bitcmp1_b32 s2, 3
	s_cbranch_scc0 .Ltf_P8_go
	s_mov_b32 s100, 1
	s_branch .LBB0_2877

.Ltf_P9_redo:
	s_add_u32 s6, s28, 0x1f00000
	v_and_b32_e32 v161, 0x3ff, v0
	s_addc_u32 s7, s29, 0
	v_bfe_u32 v162, v161, 4, 2
	v_readfirstlane_b32 s16, v161
	s_cmpk_gt_i32 s2, 0x1ff
	v_lshlrev_b32_e32 v160, 3, v162
	s_cmp_lg_u32 s100, 0
	s_cbranch_scc1 .Ltf_P9_go
	s_bitcmp1_b32 s2, 3
	s_cbranch_scc0 .Ltf_P9_go
	s_mov_b32 s100, 1
	s_branch .LBB0_2923

.Ltf_P10_redo:
	s_add_u32 s14, s28, 0xa100000
	s_addc_u32 s15, s29, 0
	s_add_u32 s4, s28, 0x2500000
	s_addc_u32 s5, s29, 0
	v_and_b32_e32 v164, 0x3ff, v0
	s_cmpk_lt_i32 s2, 0x100
	s_cselect_b64 s[6:7], -1, 0
	s_cmpk_gt_i32 s2, 0xff
	v_readfirstlane_b32 s16, v164
	s_cmp_lg_u32 s100, 0
	s_cbranch_scc1 .Ltf_P10_go
	s_bitcmp1_b32 s2, 3
	s_cbranch_scc0 .Ltf_P10_go
	s_mov_b32 s100, 1
	s_branch .LBB0_3036

.LBB0_3118:
	s_add_u32 s8, s28, 0x2700000
	v_bfe_u32 v165, v1, 4, 2
	v_cndmask_b32_e64 v2, 0, 1, s[4:5]
	s_addc_u32 s9, s29, 0
	v_lshlrev_b32_e32 v162, 4, v1
	v_and_b32_e32 v164, 15, v1
	v_cmp_ne_u32_e64 s[0:1], 1, v2
	s_andn2_b64 vcc, exec, s[4:5]
	v_lshlrev_b32_e32 v163, 3, v165
	s_cmp_lg_u32 s100, 0
	s_cbranch_scc1 .Ltf_P11_go
	s_bitcmp1_b32 s2, 3
	s_cbranch_scc0 .Ltf_P11_go
	s_mov_b32 s100, 1
	s_branch .LBB0_3186
